# scan loop: wave-uniform mask built with s_andn2 instead of v_cndmask+v_cmp; attention K-DMA: 4th address advance only in the wave that issues it (bit-identical) on top of v44
# baseline (speedup 1.0000x reference)
; #define AT_LOAD(t) do { const bf16_t* kn_ = knp + (size_t)(t) * 65536; kreg[0] = *(const u32x4*)(kn_); kreg[1] = *(const u32x4*)(kn_ + 64); kreg[2] = *(const u32x4*)(krp + (size_t)(t) * 4096); \
;                         const bf16_t* vt_ = vtp + (size_t)(t) * 65536; vreg[0] = *(const u32x4*)(vt_); vreg[1] = *(const u32x4*)(vt_ + 4096); } while (0)
; #define AT_STORE(buf) do { ldsp base_ = lds + (buf) * AT_BUF; *(LAS u32x4*)(base_ + kdst) = kreg[0]; *(LAS u32x4*)(base_ + kdst + 128) = kreg[1]; *(LAS u32x4*)(base_ + kdst + 256) = kreg[2]; \
;                            lds_w8x2(base_ + vdst, vreg[0]); lds_w8x2(base_ + vdst + 64 * AT_VP, vreg[1]); } while (0)
; DI void attn_phase(ldsp lds, const bf16_t* Q, const bf16_t* KN, const bf16_t* KR, const bf16_t* VT, bf16_t* O, int vcu, int G) {
;     ...
;             const int qb = half == 0 ? 31 - jj : jj;
;             const int q0 = qb * 256 + wid * 32;
;             bf16x8 qf[12];
;             { const bf16_t* qp = Q + (tok0 + q0 + l31) * 1536 + h * 192 + hh * 8;
; #pragma unroll
;               for (int ks = 0; ks < 12; ++ks) qf[ks] = *(const bf16x8*)(qp + ks * 16); }
;             f32x16 o[4];
; #pragma unroll
;             for (int d = 0; d < 4; ++d)
; #pragma unroll
;                 for (int r = 0; r < 16; ++r) o[d][r] = 0.f;
;             float mrun = -1e30f, lrun = 0.f;
;             const int ntiles = (qb + 1) * 4;
;             u32x4 kreg[3], vreg[2];
;             const int srow = tid >> 3, scp = tid & 7;
;             const bf16_t* knp = KN + (tok0 + srow) * 1024 + h * 128 + scp * 8;
;             const bf16_t* krp = KR + (tok0 + srow) * 64 + scp * 8;
;             const bf16_t* vtp = VT + ((tok0 >> 6) * 1024 + h * 128 + srow) * 64 + scp * 8;
;             const int kdst = srow * AT_KP + scp * 16, vdst = AT_VOFF + srow * AT_VP + scp * 16;
;     ...
;             AT_LOAD(0); AT_STORE(0); __syncthreads();
.LBB0_1448:
	s_xor_b64 s[12:13], s[14:15], -1
	s_and_b64 s[14:15], s[14:15], exec
	s_cselect_b32 s24, s23, s22
	s_lshl_b32 s25, s24, 8
	s_add_i32 s14, s25, s0
	s_ashr_i32 s15, s14, 31
	v_lshl_add_u64 v[218:219], v[198:199], 0, s[14:15]
	v_mad_u64_u32 v[2:3], s[16:17], v218, s1, v[200:201]
	v_mad_i32_i24 v3, v219, s1, v3
	v_and_b32_e32 v1, 63, v192
	s_lshl_b32 s99, s0, 1
	v_add_u32_e32 v1, s99, v1
	v_lshlrev_b32_e32 v66, 11, v174
	v_add_u32_e32 v66, v66, v176
	v_sub_co_u32_e32 v68, vcc, v202, v66
	s_nop 1
	v_subbrev_co_u32_e32 v69, vcc, 0, v203, vcc
	v_lshlrev_b32_e32 v66, 7, v174
	v_add_u32_e32 v66, v66, v176
	v_sub_co_u32_e32 v70, vcc, v204, v66
	s_nop 1
	v_subbrev_co_u32_e32 v71, vcc, 0, v205, vcc
	s_mov_b32 s99, 0xa3d70a4
	v_mov_b32_e32 v78, 0x2000
	v_mov_b32_e32 v79, 0x20000
	v_add_u32_e32 v72, 0, v1
	v_mul_hi_u32 v73, v72, s99
	v_mul_u32_u24_e32 v74, 25, v73
	v_sub_u32_e32 v74, v72, v74
	v_cmp_eq_u32_e32 vcc, 24, v74
	s_nop 1
	v_cndmask_b32_e64 v74, v74, 0, vcc
	v_cmp_lt_u32_e32 vcc, 15, v74
	v_lshlrev_b32_e32 v75, 11, v73
	v_lshl_add_u32 v75, v74, 4, v75
	v_lshlrev_b32_e32 v76, 7, v73
	v_lshl_add_u32 v76, v74, 4, v76
	v_add_u32_e32 v76, 0xffffff00, v76
	v_cndmask_b32_e32 v75, v75, v76, vcc
	v_cndmask_b32_e32 v76, v68, v70, vcc
	v_cndmask_b32_e32 v77, v69, v71, vcc
	v_cndmask_b32_e32 v134, v79, v78, vcc
	v_add_co_u32_e32 v106, vcc, v76, v75
	s_nop 1
	v_addc_co_u32_e32 v107, vcc, 0, v77, vcc
	v_add_u32_e32 v72, 512, v1
	v_mul_hi_u32 v73, v72, s99
	v_mul_u32_u24_e32 v74, 25, v73
	v_sub_u32_e32 v74, v72, v74
	v_cmp_eq_u32_e32 vcc, 24, v74
	s_nop 1
	v_cndmask_b32_e64 v74, v74, 0, vcc
	v_cmp_lt_u32_e32 vcc, 15, v74
	v_lshlrev_b32_e32 v75, 11, v73
	v_lshl_add_u32 v75, v74, 4, v75
	v_lshlrev_b32_e32 v76, 7, v73
	v_lshl_add_u32 v76, v74, 4, v76
	v_add_u32_e32 v76, 0xffffff00, v76
	v_cndmask_b32_e32 v75, v75, v76, vcc
	v_cndmask_b32_e32 v76, v68, v70, vcc
	v_cndmask_b32_e32 v77, v69, v71, vcc
	v_cndmask_b32_e32 v135, v79, v78, vcc
	v_add_co_u32_e32 v108, vcc, v76, v75
	s_nop 1
	v_addc_co_u32_e32 v109, vcc, 0, v77, vcc
	v_add_u32_e32 v72, 1024, v1
	v_mul_hi_u32 v73, v72, s99
	v_mul_u32_u24_e32 v74, 25, v73
	v_sub_u32_e32 v74, v72, v74
	v_cmp_eq_u32_e32 vcc, 24, v74
	s_nop 1
	v_cndmask_b32_e64 v74, v74, 0, vcc
	v_cmp_lt_u32_e32 vcc, 15, v74
	v_lshlrev_b32_e32 v75, 11, v73
	v_lshl_add_u32 v75, v74, 4, v75
	v_lshlrev_b32_e32 v76, 7, v73
	v_lshl_add_u32 v76, v74, 4, v76
	v_add_u32_e32 v76, 0xffffff00, v76
	v_cndmask_b32_e32 v75, v75, v76, vcc
	v_cndmask_b32_e32 v76, v68, v70, vcc
	v_cndmask_b32_e32 v77, v69, v71, vcc
	v_cndmask_b32_e32 v136, v79, v78, vcc
	v_add_co_u32_e32 v118, vcc, v76, v75
	s_nop 1
	v_addc_co_u32_e32 v119, vcc, 0, v77, vcc
	v_add_u32_e32 v72, 1536, v1
	v_mul_hi_u32 v73, v72, s99
	v_mul_u32_u24_e32 v74, 25, v73
	v_sub_u32_e32 v74, v72, v74
	v_cmp_eq_u32_e32 vcc, 24, v74
	s_nop 1
	v_cndmask_b32_e64 v74, v74, 0, vcc
	v_cmp_lt_u32_e32 vcc, 15, v74
	v_lshlrev_b32_e32 v75, 11, v73
	v_lshl_add_u32 v75, v74, 4, v75
	v_lshlrev_b32_e32 v76, 7, v73
	v_lshl_add_u32 v76, v74, 4, v76
	v_add_u32_e32 v76, 0xffffff00, v76
	v_cndmask_b32_e32 v75, v75, v76, vcc
	v_cndmask_b32_e32 v76, v68, v70, vcc
	v_cndmask_b32_e32 v77, v69, v71, vcc
	v_cndmask_b32_e32 v137, v79, v78, vcc
	v_add_co_u32_e32 v120, vcc, v76, v75
	s_nop 1
	v_addc_co_u32_e32 v121, vcc, 0, v77, vcc
	s_lshl_b32 s99, s0, 5
	s_mov_b32 m0, s99
	s_nop 0
	global_load_lds_dwordx4 v[106:107], off
	s_add_i32 m0, s99, 0x2000
	s_nop 0
	global_load_lds_dwordx4 v[108:109], off
	s_add_i32 m0, s99, 0x4000
	s_nop 0
	global_load_lds_dwordx4 v[118:119], off
	s_cmp_lg_u32 s0, 0
	s_cbranch_scc1 .Lkd_p_skip
	s_add_i32 m0, s99, 0x6000
	s_nop 0
	global_load_lds_dwordx4 v[120:121], off
	v_add_co_u32_e32 v120, vcc, v120, v137
	s_nop 1
	v_addc_co_u32_e32 v121, vcc, 0, v121, vcc
.Lkd_p_skip:
	v_add_co_u32_e32 v106, vcc, v106, v134
	s_nop 1
	v_addc_co_u32_e32 v107, vcc, 0, v107, vcc
	v_add_co_u32_e32 v108, vcc, v108, v135
	s_nop 1
	v_addc_co_u32_e32 v109, vcc, 0, v109, vcc
	v_add_co_u32_e32 v118, vcc, v118, v136
	s_nop 1
	v_addc_co_u32_e32 v119, vcc, 0, v119, vcc
	global_load_dwordx4 v[158:161], v[206:207], off
	global_load_dwordx4 v[162:165], v[208:209], off
	global_load_dwordx4 v[98:101], v[2:3], off
	global_load_dwordx4 v[102:105], v[2:3], off offset:32
	global_load_dwordx4 v[110:113], v[2:3], off offset:64
	global_load_dwordx4 v[114:117], v[2:3], off offset:96
	global_load_dwordx4 v[122:125], v[2:3], off offset:128
	global_load_dwordx4 v[126:129], v[2:3], off offset:160
	global_load_dwordx4 v[130:133], v[2:3], off offset:192
	global_load_dwordx4 v[138:141], v[2:3], off offset:224
	global_load_dwordx4 v[142:145], v[2:3], off offset:256
	global_load_dwordx4 v[146:149], v[2:3], off offset:288
	global_load_dwordx4 v[150:153], v[2:3], off offset:320
	global_load_dwordx4 v[154:157], v[2:3], off offset:352
	v_mov_b32_e32 v14, v0
	v_mov_b32_e32 v15, v0
	v_mov_b32_e32 v1, v0
	v_mov_b32_e32 v2, v0
	v_mov_b32_e32 v3, v0
	v_mov_b32_e32 v4, v0
	v_mov_b32_e32 v5, v0
	v_mov_b32_e32 v6, v0
	v_mov_b32_e32 v7, v0
	v_mov_b32_e32 v8, v0
	v_mov_b32_e32 v9, v0
	v_mov_b32_e32 v10, v0
	v_mov_b32_e32 v11, v0
	v_mov_b32_e32 v12, v0
	v_mov_b32_e32 v13, v0
	v_mov_b64_e32 v[64:65], v[14:15]
	v_mov_b64_e32 v[48:49], v[14:15]
	v_mov_b64_e32 v[32:33], v[14:15]
	s_lshl_b32 s15, s24, 2
	v_mov_b64_e32 v[62:63], v[12:13]
	v_mov_b64_e32 v[60:61], v[10:11]
	v_mov_b64_e32 v[58:59], v[8:9]
	v_mov_b64_e32 v[56:57], v[6:7]
	v_mov_b64_e32 v[54:55], v[4:5]
	v_mov_b64_e32 v[52:53], v[2:3]
	v_mov_b64_e32 v[50:51], v[0:1]
	v_mov_b64_e32 v[46:47], v[12:13]
	v_mov_b64_e32 v[44:45], v[10:11]
	v_mov_b64_e32 v[42:43], v[8:9]
	v_mov_b64_e32 v[40:41], v[6:7]
	v_mov_b64_e32 v[38:39], v[4:5]
	v_mov_b64_e32 v[36:37], v[2:3]
	v_mov_b64_e32 v[34:35], v[0:1]
	v_mov_b64_e32 v[30:31], v[12:13]
	v_mov_b64_e32 v[28:29], v[10:11]
	v_mov_b64_e32 v[26:27], v[8:9]
	v_mov_b64_e32 v[24:25], v[6:7]
	v_mov_b64_e32 v[22:23], v[4:5]
	v_mov_b64_e32 v[20:21], v[2:3]
	v_mov_b64_e32 v[18:19], v[0:1]
	v_mov_b64_e32 v[16:17], v[14:15]
	s_mov_b32 s6, 0
	v_mov_b32_e32 v229, 0xf149f2ca
	s_add_i32 s15, s15, 4
	s_add_i32 s24, s25, 0x100
	s_or_b32 s25, s14, 31
	v_or_b32_e32 v228, s14, v166
	v_mov_b32_e32 v227, 0
	s_mov_b32 s26, 1
	v_mov_b64_e32 v[220:221], v[216:217]
	v_mov_b64_e32 v[222:223], v[214:215]
	v_mov_b64_e32 v[224:225], v[212:213]
	v_mov_b64_e32 v[14:15], v[12:13]
	v_mov_b64_e32 v[12:13], v[10:11]
	v_mov_b64_e32 v[10:11], v[8:9]
	v_mov_b64_e32 v[8:9], v[6:7]
	v_mov_b64_e32 v[6:7], v[4:5]
	v_mov_b64_e32 v[4:5], v[2:3]
	v_mov_b64_e32 v[2:3], v[0:1]
	s_waitcnt vmcnt(0)
	ds_write2_b64 v187, v[158:159], v[160:161] offset1:1
	ds_write2_b64 v195, v[162:163], v[164:165] offset1:1
	s_waitcnt lgkmcnt(0)
	s_barrier
	s_branch .LBB0_1450

; #define AT_LOAD(t) do { const bf16_t* kn_ = knp + (size_t)(t) * 65536; kreg[0] = *(const u32x4*)(kn_); kreg[1] = *(const u32x4*)(kn_ + 64); kreg[2] = *(const u32x4*)(krp + (size_t)(t) * 4096); \
;                         const bf16_t* vt_ = vtp + (size_t)(t) * 65536; vreg[0] = *(const u32x4*)(vt_); vreg[1] = *(const u32x4*)(vt_ + 4096); } while (0)
; DI void attn_phase(ldsp lds, const bf16_t* Q, const bf16_t* KN, const bf16_t* KR, const bf16_t* VT, bf16_t* O, int vcu, int G) {
;     ...
;             for (int t = 0; t < ntiles; ++t) {
;                 const int buf = t & 1, key0 = t * 64;
;                 if (t + 1 < ntiles) AT_LOAD(t + 1);
;                 if (key0 <= q0 + 31) {
.LBB0_1453:
	s_and_b32 s99, s26, 1
	s_mul_i32 s99, s99, 0xa800
	s_lshl_b32 s98, s0, 5
	s_add_i32 s99, s99, s98
	s_mov_b32 m0, s99
	s_nop 0
	global_load_lds_dwordx4 v[106:107], off
	s_add_i32 m0, s99, 0x2000
	s_nop 0
	global_load_lds_dwordx4 v[108:109], off
	s_add_i32 m0, s99, 0x4000
	s_nop 0
	global_load_lds_dwordx4 v[118:119], off
	s_cmp_lg_u32 s0, 0
	s_cbranch_scc1 .Lkd_l_skip
	s_add_i32 m0, s99, 0x6000
	s_nop 0
	global_load_lds_dwordx4 v[120:121], off
	v_add_co_u32_e32 v120, vcc, v120, v137
	s_nop 1
	v_addc_co_u32_e32 v121, vcc, 0, v121, vcc
.Lkd_l_skip:
	v_add_co_u32_e32 v106, vcc, v106, v134
	s_nop 1
	v_addc_co_u32_e32 v107, vcc, 0, v107, vcc
	v_add_co_u32_e32 v108, vcc, v108, v135
	s_nop 1
	v_addc_co_u32_e32 v109, vcc, 0, v109, vcc
	v_add_co_u32_e32 v118, vcc, v118, v136
	s_nop 1
	v_addc_co_u32_e32 v119, vcc, 0, v119, vcc
	v_lshl_add_u64 v[66:67], v[220:221], 0, v[176:177]
	v_add_co_u32_e32 v68, vcc, 0x38020000, v66
	s_nop 1
	v_addc_co_u32_e32 v69, vcc, 0, v67, vcc
	v_add_co_u32_e32 v66, vcc, 0x38022000, v66
	s_nop 1
	v_addc_co_u32_e32 v67, vcc, 0, v67, vcc
	global_load_dwordx4 v[158:161], v[68:69], off
	global_load_dwordx4 v[162:165], v[66:67], off
	s_add_i32 s27, s26, -1
	s_and_b32 s27, s27, 1
	s_cmp_gt_i32 s6, s25
	s_cbranch_scc1 .LBB0_1452

; #define LAS __attribute__((address_space(3)))
; DI void hgrn_scan(ldsp lds, const bf16_t* QT, const bf16_t* KT, const bf16_t* KHT, const bf16_t* HVT, const float* DEC, bf16_t* HO, int vcu, int G) {
;     ...
;             ldsp qb_ = Lb + HS_QT + (tb * 32 + l31) * HS_QP + db * 64 + hh * 16; ldsp kb_ = Lb + HS_KT + l31 * HS_QP + db * 64 + hh * 16;
;             ldsp qr_ = Lb + HS_QT + (tb * 32 + l31) * HS_QP + 8 * hh + db * 64; ldsp vr_ = Lb + HS_VT + l31 * HS_P + 8 * hh;
;             const bf16x8 qv0 = *(const LAS bf16x8*)(qb_), qv1 = *(const LAS bf16x8*)(qb_ + 32), k00 = *(const LAS bf16x8*)(kb_), k01 = *(const LAS bf16x8*)(kb_ + 32);
;             const bf16x8 qa0 = lds_8x2(qr_, 16), qa1 = lds_8x2(qr_ + 32, 16), v00 = lds_8x2(vr_, 16), v01 = lds_8x2(vr_ + 32, 16);
;             bf16x8 k10 = k00, k11 = k01, v10 = v00, v11 = v01;
;             if (tb == 1) { k10 = *(const LAS bf16x8*)(kb_ + 32 * HS_QP); k11 = *(const LAS bf16x8*)(kb_ + 32 * HS_QP + 32); v10 = lds_8x2(vr_ + 64, 16); v11 = lds_8x2(vr_ + 96, 16); }
.LBB0_2075:
	s_or_b64 exec, exec, s[8:9]
	v_add_u32_e32 v28, v174, v147
	v_add_u32_e32 v28, 0xc800, v28
	ds_read_b128 v[88:91], v223
	ds_read_b128 v[84:87], v223 offset:32
	ds_read_b128 v[24:27], v224 offset:17408
	ds_read_b128 v[20:23], v224 offset:17440
	ds_read2_b64 v[16:19], v225 offset1:2
	ds_read2_b64 v[112:115], v225 offset0:4 offset1:6
	ds_read2_b64 v[108:111], v28 offset0:128 offset1:130
	ds_read2_b64 v[96:99], v28 offset0:132 offset1:134
	s_waitcnt lgkmcnt(4)
	s_andn2_b64 s[8:9], exec, s[80:81]
	s_andn2_b64 vcc, exec, s[80:81]
	s_waitcnt lgkmcnt(0)
	s_cbranch_vccnz .LBB0_2077
	ds_read_b128 v[104:107], v224 offset:26112
	ds_read_b128 v[100:103], v224 offset:26144
	ds_read2_b64 v[92:95], v28 offset0:136 offset1:138
	ds_read2_b64 v[80:83], v28 offset0:140 offset1:142
